# guide 7.12: DSA candidate test branches on SCC of the mask OR; ballot copies only on the append path; stale s_nop after scalar FMAs removed
# baseline (speedup 1.0000x reference)
; DI u32 mono_key(float f) { u32 u = __float_as_uint(f); return (u & 0x80000000u) ? ~u : (u | 0x80000000u); }
; DI void dsa_item(const Params& p, int l, int tile32, int b, char* smem) {
;     ...
;         const u32 k0 = mono_key(s0), k1 = mono_key(s1);
;         const bool c0 = (key <= qpos0) && (k0 > tauA), c1 = (key <= qpos0 + 1) && (k1 > tauB);
;         const u64 m0 = __ballot(c0), m1 = __ballot(c1);
;         if (m0 | m1) {
;           const u32 h0 = hh ? (u32)(m0 >> 32) : (u32)m0, h1 = hh ? (u32)(m1 >> 32) : (u32)m1;
;           const int pA = (hh ? cnt2 : cnt0) + __popc(h0 & lmask), pB = (hh ? cnt3 : cnt1) + __popc(h1 & lmask);
;           if (c0) { ckey[(2 * hh) * DCAP + pA] = k0; cidx[(2 * hh) * DCAP + pA] = (u16)key; }
;           if (c1) { ckey[(2 * hh + 1) * DCAP + pB] = k1; cidx[(2 * hh + 1) * DCAP + pB] = (u16)key; }
;           cnt0 += __popc((u32)m0); cnt2 += __popc((u32)(m0 >> 32));
;           cnt1 += __popc((u32)m1); cnt3 += __popc((u32)(m1 >> 32));
;         }
.LBB0_499:
	s_or_b64 exec, exec, s[2:3]
	v_mfma_f32_32x32x16_bf16 v[2:17], v[18:21], v[2:5], 0
	v_cndmask_b32_e32 v0, v223, v224, vcc
	v_mfma_f32_32x32x16_bf16 v[2:17], v[22:25], v[98:101], v[2:17]
	v_mfma_f32_32x32x16_bf16 v[2:17], v[26:29], v[94:97], v[2:17]
	v_lshl_or_b32 v95, s54, 7, v192
	v_cndmask_b32_e32 v94, v221, v222, vcc
	v_cmp_le_i32_e64 s[0:1], v95, v217
	v_cmp_le_i32_e64 s[2:3], v95, v219
	v_mfma_f32_32x32x16_bf16 v[2:17], v[30:33], v[90:93], v[2:17]
	s_nop 11
	v_med3_f32 v2, v2, 0, v204
	v_med3_f32 v3, v3, 0, v204
	v_med3_f32 v4, v4, 0, v204
	v_med3_f32 v5, v5, 0, v204
	v_fma_f32 v2, v178, v2, 0
	v_fma_f32 v3, v179, v3, 0
	v_med3_f32 v6, v6, 0, v204
	v_med3_f32 v7, v7, 0, v204
	v_fmac_f32_e32 v2, v38, v4
	v_fmac_f32_e32 v3, v39, v5
	v_med3_f32 v8, v8, 0, v204
	v_med3_f32 v9, v9, 0, v204
	v_fmac_f32_e32 v2, v180, v6
	v_fmac_f32_e32 v3, v181, v7
	v_med3_f32 v10, v10, 0, v204
	v_med3_f32 v11, v11, 0, v204
	v_fmac_f32_e32 v2, v40, v8
	v_fmac_f32_e32 v3, v41, v9
	v_med3_f32 v12, v12, 0, v204
	v_med3_f32 v13, v13, 0, v204
	v_fmac_f32_e32 v2, v182, v10
	v_fmac_f32_e32 v3, v183, v11
	v_med3_f32 v14, v14, 0, v204
	v_med3_f32 v15, v15, 0, v204
	v_fmac_f32_e32 v2, v34, v12
	v_fmac_f32_e32 v3, v35, v13
	v_med3_f32 v16, v16, 0, v204
	v_med3_f32 v17, v17, 0, v204
	v_fmac_f32_e32 v2, v184, v14
	v_fmac_f32_e32 v3, v185, v15
	v_fma_f32 v4, v36, v16, v2
	v_fma_f32 v5, v37, v17, v3
	v_ashrrev_i32_e32 v2, 31, v4
	v_ashrrev_i32_e32 v6, 31, v5
	v_or_b32_e32 v2, 0x80000000, v2
	v_or_b32_e32 v6, 0x80000000, v6
	v_xor_b32_e32 v3, v4, v2
	v_xor_b32_e32 v2, v5, v6
	v_cmp_gt_u32_e64 s[4:5], v3, v0
	v_cmp_gt_u32_e64 s[6:7], v2, v94
	s_and_b64 s[10:11], s[0:1], s[4:5]
	s_and_b64 s[4:5], s[2:3], s[6:7]
	s_or_b64 s[6:7], s[10:11], s[4:5]
	s_cbranch_scc0 .LBB0_505
	s_and_b64 s[0:1], s[10:11], exec
	s_and_b64 s[2:3], s[4:5], exec
	s_and_saveexec_b64 s[6:7], s[10:11]
	s_cbranch_execz .LBB0_502
	v_mov_b32_e32 v4, s1
	v_mov_b32_e32 v5, s0
	v_cndmask_b32_e32 v4, v4, v5, vcc
	v_and_b32_e32 v4, v4, v218
	v_bcnt_u32_b32 v4, v4, 0
	v_cndmask_b32_e32 v5, v187, v173, vcc
	v_add3_u32 v4, v5, v214, v4
	v_lshl_add_u32 v5, v4, 2, v190
	ds_write_b32 v5, v3
	v_lshlrev_b32_e32 v3, 1, v4
	v_sub_u32_e32 v3, v5, v3
	ds_write_b16 v3, v95 offset:10240

; DI u32 mono_key(float f) { u32 u = __float_as_uint(f); return (u & 0x80000000u) ? ~u : (u | 0x80000000u); }
; DI void dsa_item(const Params& p, int l, int tile32, int b, char* smem) {
;     ...
;         const u32 k0 = mono_key(s0), k1 = mono_key(s1);
;         const bool c0 = (key <= qpos0) && (k0 > tauA), c1 = (key <= qpos0 + 1) && (k1 > tauB);
;         const u64 m0 = __ballot(c0), m1 = __ballot(c1);
;         if (m0 | m1) {
;           const u32 h0 = hh ? (u32)(m0 >> 32) : (u32)m0, h1 = hh ? (u32)(m1 >> 32) : (u32)m1;
;           const int pA = (hh ? cnt2 : cnt0) + __popc(h0 & lmask), pB = (hh ? cnt3 : cnt1) + __popc(h1 & lmask);
;           if (c0) { ckey[(2 * hh) * DCAP + pA] = k0; cidx[(2 * hh) * DCAP + pA] = (u16)key; }
;           if (c1) { ckey[(2 * hh + 1) * DCAP + pB] = k1; cidx[(2 * hh + 1) * DCAP + pB] = (u16)key; }
;           cnt0 += __popc((u32)m0); cnt2 += __popc((u32)(m0 >> 32));
;           cnt1 += __popc((u32)m1); cnt3 += __popc((u32)(m1 >> 32));
;         }
.LBB0_505:
	v_mfma_f32_32x32x16_bf16 v[2:17], v[18:21], v[86:89], 0
	v_mfma_f32_32x32x16_bf16 v[2:17], v[22:25], v[82:85], v[2:17]
	v_mfma_f32_32x32x16_bf16 v[2:17], v[26:29], v[78:81], v[2:17]
	v_or_b32_e32 v78, 32, v95
	v_cmp_le_i32_e64 s[0:1], v78, v217
	v_cmp_le_i32_e64 s[2:3], v78, v219
	v_mfma_f32_32x32x16_bf16 v[2:17], v[30:33], v[74:77], v[2:17]
	s_nop 11
	v_med3_f32 v2, v2, 0, v204
	v_med3_f32 v3, v3, 0, v204
	v_med3_f32 v4, v4, 0, v204
	v_med3_f32 v5, v5, 0, v204
	v_fma_f32 v2, v178, v2, 0
	v_fma_f32 v3, v179, v3, 0
	v_med3_f32 v6, v6, 0, v204
	v_med3_f32 v7, v7, 0, v204
	v_fmac_f32_e32 v2, v38, v4
	v_fmac_f32_e32 v3, v39, v5
	v_med3_f32 v8, v8, 0, v204
	v_med3_f32 v9, v9, 0, v204
	v_fmac_f32_e32 v2, v180, v6
	v_fmac_f32_e32 v3, v181, v7
	v_med3_f32 v10, v10, 0, v204
	v_med3_f32 v11, v11, 0, v204
	v_fmac_f32_e32 v2, v40, v8
	v_fmac_f32_e32 v3, v41, v9
	v_med3_f32 v12, v12, 0, v204
	v_med3_f32 v13, v13, 0, v204
	v_fmac_f32_e32 v2, v182, v10
	v_fmac_f32_e32 v3, v183, v11
	v_med3_f32 v14, v14, 0, v204
	v_med3_f32 v15, v15, 0, v204
	v_fmac_f32_e32 v2, v34, v12
	v_fmac_f32_e32 v3, v35, v13
	v_med3_f32 v16, v16, 0, v204
	v_med3_f32 v17, v17, 0, v204
	v_fmac_f32_e32 v2, v184, v14
	v_fmac_f32_e32 v3, v185, v15
	v_fma_f32 v4, v36, v16, v2
	v_fma_f32 v5, v37, v17, v3
	v_ashrrev_i32_e32 v2, 31, v4
	v_ashrrev_i32_e32 v6, 31, v5
	v_or_b32_e32 v2, 0x80000000, v2
	v_or_b32_e32 v6, 0x80000000, v6
	v_xor_b32_e32 v3, v4, v2
	v_xor_b32_e32 v2, v5, v6
	v_cmp_gt_u32_e64 s[4:5], v3, v0
	v_cmp_gt_u32_e64 s[6:7], v2, v94
	s_and_b64 s[10:11], s[0:1], s[4:5]
	s_and_b64 s[4:5], s[2:3], s[6:7]
	s_or_b64 s[6:7], s[10:11], s[4:5]
	s_cbranch_scc0 .LBB0_511
	s_and_b64 s[2:3], s[10:11], exec
	s_and_b64 s[0:1], s[4:5], exec
	s_and_saveexec_b64 s[6:7], s[10:11]
	s_cbranch_execz .LBB0_508
	v_mov_b32_e32 v4, s3
	v_mov_b32_e32 v5, s2
	v_cndmask_b32_e32 v4, v4, v5, vcc
	v_and_b32_e32 v4, v4, v218
	v_bcnt_u32_b32 v4, v4, 0
	v_cndmask_b32_e32 v5, v187, v173, vcc
	v_add3_u32 v4, v5, v214, v4
	v_lshl_add_u32 v5, v4, 2, v190
	ds_write_b32 v5, v3
	v_lshlrev_b32_e32 v3, 1, v4
	v_sub_u32_e32 v3, v5, v3
	ds_write_b16 v3, v78 offset:10240

; DI u32 mono_key(float f) { u32 u = __float_as_uint(f); return (u & 0x80000000u) ? ~u : (u | 0x80000000u); }
; DI void dsa_item(const Params& p, int l, int tile32, int b, char* smem) {
;     ...
;         const u32 k0 = mono_key(s0), k1 = mono_key(s1);
;         const bool c0 = (key <= qpos0) && (k0 > tauA), c1 = (key <= qpos0 + 1) && (k1 > tauB);
;         const u64 m0 = __ballot(c0), m1 = __ballot(c1);
;         if (m0 | m1) {
;           const u32 h0 = hh ? (u32)(m0 >> 32) : (u32)m0, h1 = hh ? (u32)(m1 >> 32) : (u32)m1;
;           const int pA = (hh ? cnt2 : cnt0) + __popc(h0 & lmask), pB = (hh ? cnt3 : cnt1) + __popc(h1 & lmask);
;           if (c0) { ckey[(2 * hh) * DCAP + pA] = k0; cidx[(2 * hh) * DCAP + pA] = (u16)key; }
;           if (c1) { ckey[(2 * hh + 1) * DCAP + pB] = k1; cidx[(2 * hh + 1) * DCAP + pB] = (u16)key; }
;           cnt0 += __popc((u32)m0); cnt2 += __popc((u32)(m0 >> 32));
;           cnt1 += __popc((u32)m1); cnt3 += __popc((u32)(m1 >> 32));
;         }
.LBB0_511:
	v_mfma_f32_32x32x16_bf16 v[2:17], v[18:21], v[70:73], 0
	v_mfma_f32_32x32x16_bf16 v[2:17], v[22:25], v[66:69], v[2:17]
	v_mfma_f32_32x32x16_bf16 v[2:17], v[26:29], v[62:65], v[2:17]
	v_or_b32_e32 v62, 64, v95
	v_cmp_le_i32_e64 s[0:1], v62, v217
	v_cmp_le_i32_e64 s[2:3], v62, v219
	v_mfma_f32_32x32x16_bf16 v[2:17], v[30:33], v[58:61], v[2:17]
	s_nop 11
	v_med3_f32 v2, v2, 0, v204
	v_med3_f32 v3, v3, 0, v204
	v_med3_f32 v4, v4, 0, v204
	v_med3_f32 v5, v5, 0, v204
	v_fma_f32 v2, v178, v2, 0
	v_fma_f32 v3, v179, v3, 0
	v_med3_f32 v6, v6, 0, v204
	v_med3_f32 v7, v7, 0, v204
	v_fmac_f32_e32 v2, v38, v4
	v_fmac_f32_e32 v3, v39, v5
	v_med3_f32 v8, v8, 0, v204
	v_med3_f32 v9, v9, 0, v204
	v_fmac_f32_e32 v2, v180, v6
	v_fmac_f32_e32 v3, v181, v7
	v_med3_f32 v10, v10, 0, v204
	v_med3_f32 v11, v11, 0, v204
	v_fmac_f32_e32 v2, v40, v8
	v_fmac_f32_e32 v3, v41, v9
	v_med3_f32 v12, v12, 0, v204
	v_med3_f32 v13, v13, 0, v204
	v_fmac_f32_e32 v2, v182, v10
	v_fmac_f32_e32 v3, v183, v11
	v_med3_f32 v14, v14, 0, v204
	v_med3_f32 v15, v15, 0, v204
	v_fmac_f32_e32 v2, v34, v12
	v_fmac_f32_e32 v3, v35, v13
	v_med3_f32 v16, v16, 0, v204
	v_med3_f32 v17, v17, 0, v204
	v_fmac_f32_e32 v2, v184, v14
	v_fmac_f32_e32 v3, v185, v15
	v_fma_f32 v4, v36, v16, v2
	v_fma_f32 v5, v37, v17, v3
	v_ashrrev_i32_e32 v2, 31, v4
	v_ashrrev_i32_e32 v6, 31, v5
	v_or_b32_e32 v2, 0x80000000, v2
	v_or_b32_e32 v6, 0x80000000, v6
	v_xor_b32_e32 v3, v4, v2
	v_xor_b32_e32 v2, v5, v6
	v_cmp_gt_u32_e64 s[4:5], v3, v0
	v_cmp_gt_u32_e64 s[6:7], v2, v94
	s_and_b64 s[10:11], s[0:1], s[4:5]
	s_and_b64 s[4:5], s[2:3], s[6:7]
	s_or_b64 s[6:7], s[10:11], s[4:5]
	s_cbranch_scc0 .LBB0_517
	s_and_b64 s[2:3], s[10:11], exec
	s_and_b64 s[0:1], s[4:5], exec
	s_and_saveexec_b64 s[6:7], s[10:11]
	s_cbranch_execz .LBB0_514
	v_mov_b32_e32 v4, s3
	v_mov_b32_e32 v5, s2
	v_cndmask_b32_e32 v4, v4, v5, vcc
	v_and_b32_e32 v4, v4, v218
	v_bcnt_u32_b32 v4, v4, 0
	v_cndmask_b32_e32 v5, v187, v173, vcc
	v_add3_u32 v4, v5, v214, v4
	v_lshl_add_u32 v5, v4, 2, v190
	ds_write_b32 v5, v3
	v_lshlrev_b32_e32 v3, 1, v4
	v_sub_u32_e32 v3, v5, v3
	ds_write_b16 v3, v62 offset:10240

; DI u32 mono_key(float f) { u32 u = __float_as_uint(f); return (u & 0x80000000u) ? ~u : (u | 0x80000000u); }
; DI void dsa_item(const Params& p, int l, int tile32, int b, char* smem) {
;     ...
;         const u32 k0 = mono_key(s0), k1 = mono_key(s1);
;         const bool c0 = (key <= qpos0) && (k0 > tauA), c1 = (key <= qpos0 + 1) && (k1 > tauB);
;         const u64 m0 = __ballot(c0), m1 = __ballot(c1);
;         if (m0 | m1) {
;           const u32 h0 = hh ? (u32)(m0 >> 32) : (u32)m0, h1 = hh ? (u32)(m1 >> 32) : (u32)m1;
;           const int pA = (hh ? cnt2 : cnt0) + __popc(h0 & lmask), pB = (hh ? cnt3 : cnt1) + __popc(h1 & lmask);
;           if (c0) { ckey[(2 * hh) * DCAP + pA] = k0; cidx[(2 * hh) * DCAP + pA] = (u16)key; }
;           if (c1) { ckey[(2 * hh + 1) * DCAP + pB] = k1; cidx[(2 * hh + 1) * DCAP + pB] = (u16)key; }
;           cnt0 += __popc((u32)m0); cnt2 += __popc((u32)(m0 >> 32));
;           cnt1 += __popc((u32)m1); cnt3 += __popc((u32)(m1 >> 32));
;         }
.LBB0_517:
	v_mfma_f32_32x32x16_bf16 v[2:17], v[18:21], v[54:57], 0
	v_mfma_f32_32x32x16_bf16 v[2:17], v[22:25], v[50:53], v[2:17]
	v_mfma_f32_32x32x16_bf16 v[2:17], v[26:29], v[46:49], v[2:17]
	v_or_b32_e32 v46, 0x60, v95
	v_cmp_le_i32_e64 s[0:1], v46, v217
	v_cmp_le_i32_e64 s[2:3], v46, v219
	v_mfma_f32_32x32x16_bf16 v[2:17], v[30:33], v[42:45], v[2:17]
	s_nop 11
	v_med3_f32 v2, v2, 0, v204
	v_med3_f32 v3, v3, 0, v204
	v_med3_f32 v4, v4, 0, v204
	v_med3_f32 v5, v5, 0, v204
	v_fma_f32 v2, v178, v2, 0
	v_fma_f32 v3, v179, v3, 0
	v_med3_f32 v6, v6, 0, v204
	v_med3_f32 v7, v7, 0, v204
	v_fmac_f32_e32 v2, v38, v4
	v_fmac_f32_e32 v3, v39, v5
	v_med3_f32 v8, v8, 0, v204
	v_med3_f32 v9, v9, 0, v204
	v_fmac_f32_e32 v2, v180, v6
	v_fmac_f32_e32 v3, v181, v7
	v_med3_f32 v10, v10, 0, v204
	v_med3_f32 v11, v11, 0, v204
	v_fmac_f32_e32 v2, v40, v8
	v_fmac_f32_e32 v3, v41, v9
	v_med3_f32 v12, v12, 0, v204
	v_med3_f32 v13, v13, 0, v204
	v_fmac_f32_e32 v2, v182, v10
	v_fmac_f32_e32 v3, v183, v11
	v_med3_f32 v14, v14, 0, v204
	v_med3_f32 v15, v15, 0, v204
	v_fmac_f32_e32 v2, v34, v12
	v_fmac_f32_e32 v3, v35, v13
	v_med3_f32 v16, v16, 0, v204
	v_med3_f32 v17, v17, 0, v204
	v_fmac_f32_e32 v2, v184, v14
	v_fmac_f32_e32 v3, v185, v15
	v_fma_f32 v4, v36, v16, v2
	v_fma_f32 v5, v37, v17, v3
	v_ashrrev_i32_e32 v2, 31, v4
	v_ashrrev_i32_e32 v6, 31, v5
	v_or_b32_e32 v2, 0x80000000, v2
	v_or_b32_e32 v6, 0x80000000, v6
	v_xor_b32_e32 v3, v4, v2
	v_xor_b32_e32 v2, v5, v6
	v_cmp_gt_u32_e64 s[4:5], v3, v0
	v_cmp_gt_u32_e64 s[6:7], v2, v94
	s_and_b64 s[10:11], s[0:1], s[4:5]
	s_and_b64 s[4:5], s[2:3], s[6:7]
	s_or_b64 s[6:7], s[10:11], s[4:5]
	s_cbranch_scc0 .LBB0_374
	s_and_b64 s[2:3], s[10:11], exec
	s_and_b64 s[0:1], s[4:5], exec
	s_and_saveexec_b64 s[6:7], s[10:11]
	s_cbranch_execz .LBB0_520
	v_mov_b32_e32 v0, s3
	v_mov_b32_e32 v4, s2
	v_cndmask_b32_e32 v0, v0, v4, vcc
	v_and_b32_e32 v0, v0, v218
	v_bcnt_u32_b32 v0, v0, 0
	v_cndmask_b32_e32 v4, v187, v173, vcc
	v_add3_u32 v0, v4, v214, v0
	v_lshl_add_u32 v4, v0, 2, v190
	v_lshlrev_b32_e32 v0, 1, v0
	v_sub_u32_e32 v0, v4, v0
	ds_write_b32 v4, v3
	ds_write_b16 v0, v46 offset:10240
